# conversion loops: gain pairs loaded before the tile loads and applied at the top of the next iteration (sites after FFN-up, attention phase, residual GEMMs)
# baseline (speedup 1.0000x reference)
; __device__ __forceinline__ void tr_load(const TrJob& jb, int tile, int tid, f32x4 (&v)[8][2], int& k0, int& n0) {
;     const int nblk = (jb.N + 127) / 128, kt = tile / nblk, nt = tile - kt * nblk; k0 = 256 * kt; n0 = 128 * nt;
;     const int c4 = (tid & 15) + 16 * ((tid >> 6) & 1), rp = ((tid >> 4) & 3) + 4 * (tid >> 7);
;     int col = n0 + 4 * c4; col = col < jb.N - 4 ? col : jb.N - 4;
;     const float* wp = jb.W + (size_t)(k0 + 2 * rp) * jb.N + col;
; #pragma unroll
;     for (int i = 0; i < 8; ++i) { v[i][0] = *(const f32x4*)(wp + (size_t)(32 * i) * jb.N); v[i][1] = *(const f32x4*)(wp + (size_t)(32 * i + 1) * jb.N); }
;     if (jb.gain) {
; #pragma unroll
;         for (int i = 0; i < 8; ++i) { const float ga = jb.gain[k0 + 32 * i + 2 * rp], gb = jb.gain[k0 + 32 * i + 2 * rp + 1]; v[i][0] = v[i][0] * ga; v[i][1] = v[i][1] * gb; } }
; }
.LBB0_343:
	s_add_i32 s6, s34, 0x7f
	s_lshr_b32 s6, s6, 7
	v_cvt_f32_u32_e32 v4, s6
	s_sub_i32 s9, 0, s6
	s_abs_i32 s8, s15
	s_ashr_i32 s7, s15, 31
	v_rcp_iflag_f32_e32 v4, v4
	v_lshrrev_b32_e32 v5, 4, v2
	v_ashrrev_i32_e32 v71, 5, v2
	v_bfi_b32 v5, 3, v5, v71
	v_mul_f32_e32 v4, 0x4f7ffffe, v4
	v_cvt_u32_f32_e32 v4, v4
	v_and_b32_e32 v70, 64, v2
	v_lshlrev_b32_e32 v78, 1, v5
	v_readfirstlane_b32 s12, v4
	s_mul_i32 s9, s9, s12
	s_mul_hi_u32 s9, s12, s9
	s_add_i32 s12, s12, s9
	s_mul_hi_u32 s9, s8, s12
	s_mul_i32 s12, s9, s6
	s_sub_i32 s8, s8, s12
	s_add_i32 s13, s9, 1
	s_sub_i32 s12, s8, s6
	s_cmp_ge_u32 s8, s6
	s_cselect_b32 s9, s13, s9
	s_cselect_b32 s8, s12, s8
	s_add_i32 s12, s9, 1
	s_cmp_ge_u32 s8, s6
	s_cselect_b32 s8, s12, s9
	s_xor_b32 s8, s8, s7
	s_sub_i32 s7, s8, s7
	s_mul_i32 s6, s7, s6
	s_sub_i32 s6, s15, s6
	v_lshlrev_b32_e32 v4, 2, v2
	s_lshl_b32 s14, s7, 8
	s_lshl_b32 s15, s6, 7
	v_and_or_b32 v77, v4, 60, v70
	v_or_b32_e32 v4, s15, v77
	s_add_i32 s6, s34, -4
	v_add_u32_e32 v68, s14, v78
	v_min_i32_e32 v4, s6, v4
	s_waitcnt vmcnt(12)
	v_mad_u64_u32 v[6:7], s[6:7], v68, s34, 0
	v_ashrrev_i32_e32 v69, 31, v68
	v_mov_b32_e32 v8, v7
	v_mad_u64_u32 v[8:9], s[6:7], v69, s34, v[8:9]
	v_mov_b32_e32 v7, v8
	v_lshl_add_u64 v[6:7], v[6:7], 2, s[4:5]
	v_ashrrev_i32_e32 v5, 31, v4
	v_lshl_add_u64 v[4:5], v[4:5], 2, v[6:7]
	s_lshl_b64 s[4:5], s[34:35], 2
	s_waitcnt vmcnt(11)
	v_lshl_add_u64 v[12:13], v[4:5], 0, s[4:5]
	s_mul_i32 s6, s34, 0x7c
	s_mov_b32 s7, s35
	s_mov_b32 s63, 0
	s_cmp_eq_u64 s[10:11], 0
	s_cbranch_scc1 .Lgf__347_7241
	s_mov_b32 s63, 1
	v_lshl_add_u64 v[112:113], v[68:69], 2, s[10:11]
	global_load_dwordx2 v[96:97], v[112:113], off
	global_load_dwordx2 v[98:99], v[112:113], off offset:128
	global_load_dwordx2 v[100:101], v[112:113], off offset:256
	global_load_dwordx2 v[102:103], v[112:113], off offset:384
	global_load_dwordx2 v[104:105], v[112:113], off offset:512
	global_load_dwordx2 v[106:107], v[112:113], off offset:640
	global_load_dwordx2 v[108:109], v[112:113], off offset:768
	global_load_dwordx2 v[110:111], v[112:113], off offset:896
.Lgf__347_7241:
	global_load_dwordx4 v[4:7], v[4:5], off sc1 nt
	s_nop 0
	global_load_dwordx4 v[8:11], v[12:13], off sc1 nt
	v_lshl_add_u64 v[12:13], v[12:13], 0, s[6:7]
	s_waitcnt vmcnt(11)
	v_lshl_add_u64 v[20:21], v[12:13], 0, s[4:5]
	global_load_dwordx4 v[12:15], v[12:13], off sc1 nt
	s_nop 0
	global_load_dwordx4 v[16:19], v[20:21], off sc1 nt
	v_lshl_add_u64 v[20:21], v[20:21], 0, s[6:7]
	s_waitcnt vmcnt(12)
	v_lshl_add_u64 v[28:29], v[20:21], 0, s[4:5]
	global_load_dwordx4 v[20:23], v[20:21], off sc1 nt
	s_nop 0
	global_load_dwordx4 v[24:27], v[28:29], off sc1 nt
	v_lshl_add_u64 v[28:29], v[28:29], 0, s[6:7]
	s_waitcnt vmcnt(13)
	v_lshl_add_u64 v[36:37], v[28:29], 0, s[4:5]
	s_waitcnt vmcnt(12)
	v_lshl_add_u64 v[40:41], v[36:37], 0, s[6:7]
	s_waitcnt vmcnt(11)
	v_lshl_add_u64 v[44:45], v[40:41], 0, s[4:5]
	s_waitcnt vmcnt(10)
	v_lshl_add_u64 v[48:49], v[44:45], 0, s[6:7]
	s_waitcnt vmcnt(9)
	v_lshl_add_u64 v[52:53], v[48:49], 0, s[4:5]
	s_waitcnt vmcnt(8)
	v_lshl_add_u64 v[56:57], v[52:53], 0, s[6:7]
	s_waitcnt vmcnt(7)
	v_lshl_add_u64 v[60:61], v[56:57], 0, s[4:5]
	s_waitcnt vmcnt(6)
	v_lshl_add_u64 v[64:65], v[60:61], 0, s[6:7]
	global_load_dwordx4 v[28:31], v[28:29], off sc1 nt
	s_nop 0
	global_load_dwordx4 v[32:35], v[36:37], off sc1 nt
	s_cmp_eq_u64 s[10:11], 0
	global_load_dwordx4 v[36:39], v[40:41], off sc1 nt
	s_nop 0
	global_load_dwordx4 v[40:43], v[44:45], off sc1 nt
	s_nop 0
	global_load_dwordx4 v[44:47], v[48:49], off sc1 nt
	s_nop 0
	global_load_dwordx4 v[48:51], v[52:53], off sc1 nt
	s_nop 0
	global_load_dwordx4 v[52:55], v[56:57], off sc1 nt
	s_nop 0
	global_load_dwordx4 v[56:59], v[60:61], off sc1 nt
	s_nop 0
	global_load_dwordx4 v[60:63], v[64:65], off sc1 nt
	v_lshl_add_u64 v[64:65], v[64:65], 0, s[4:5]
	global_load_dwordx4 v[64:67], v[64:65], off sc1 nt

; #define LAS __attribute__((address_space(3)))
; __device__ __forceinline__ unsigned pk2(float lo, float hi) { return f2bf(lo) | (f2bf(hi) << 16); }
; __device__ __forceinline__ void tr_load(const TrJob& jb, int tile, int tid, f32x4 (&v)[8][2], int& k0, int& n0) {
;     ...
;     if (jb.gain) {
; #pragma unroll
;         for (int i = 0; i < 8; ++i) { const float ga = jb.gain[k0 + 32 * i + 2 * rp], gb = jb.gain[k0 + 32 * i + 2 * rp + 1]; v[i][0] = v[i][0] * ga; v[i][1] = v[i][1] * gb; } }
; }
; __device__ __forceinline__ void tr_to_lds(LAS unsigned* T, int tid, const f32x4 (&v)[8][2]) {
;     const int c4 = (tid & 15) + 16 * ((tid >> 6) & 1), rp = ((tid >> 4) & 3) + 4 * (tid >> 7);
; #pragma unroll
;     for (int i = 0; i < 8; ++i)
; #pragma unroll
;         for (int j = 0; j < 4; ++j) T[(4 * c4 + j) * 132 + 16 * i + rp] = pk2(v[i][0][j], v[i][1][j]);
.LBB0_347:
	s_waitcnt vmcnt(15)
	s_cmp_lg_u32 s63, 0
	s_cbranch_scc0 .Lgm__347_0
	v_pk_mul_f32 v[6:7], v[6:7], v[96:97] op_sel_hi:[1,0]
	v_pk_mul_f32 v[4:5], v[4:5], v[96:97] op_sel_hi:[1,0]
.Lgm__347_0:
	v_bfe_u32 v2, v4, 16, 1
	v_add3_u32 v2, v4, v2, s81
	s_waitcnt vmcnt(14)
	s_cmp_lg_u32 s63, 0
	s_cbranch_scc0 .Lgm__347_1
	v_pk_mul_f32 v[10:11], v[10:11], v[96:97] op_sel:[0,1]
	v_pk_mul_f32 v[8:9], v[8:9], v[96:97] op_sel:[0,1]
.Lgm__347_1:
	v_bfe_u32 v68, v8, 16, 1
	v_lshrrev_b32_e32 v2, 16, v2
	v_add3_u32 v68, v8, v68, s81
	v_and_or_b32 v2, v68, s82, v2
	v_bfe_u32 v68, v5, 16, 1
	v_add3_u32 v68, v5, v68, s81
	v_bfe_u32 v69, v9, 16, 1
	v_lshrrev_b32_e32 v68, 16, v68
	v_add3_u32 v69, v9, v69, s81
	v_and_or_b32 v68, v69, s82, v68
	v_bfe_u32 v69, v6, 16, 1
	v_add3_u32 v69, v6, v69, s81
	v_bfe_u32 v70, v10, 16, 1
	v_lshrrev_b32_e32 v69, 16, v69
	v_add3_u32 v70, v10, v70, s81
	v_and_or_b32 v69, v70, s82, v69
	v_bfe_u32 v70, v7, 16, 1
	v_add3_u32 v70, v7, v70, s81
	v_bfe_u32 v71, v11, 16, 1
	v_lshrrev_b32_e32 v70, 16, v70
	v_add3_u32 v71, v11, v71, s81
	v_and_or_b32 v70, v71, s82, v70
	s_waitcnt vmcnt(13)
	s_cmp_lg_u32 s63, 0
	s_cbranch_scc0 .Lgm__347_2
	v_pk_mul_f32 v[14:15], v[14:15], v[98:99] op_sel_hi:[1,0]
	v_pk_mul_f32 v[12:13], v[12:13], v[98:99] op_sel_hi:[1,0]
.Lgm__347_2:
	v_bfe_u32 v71, v12, 16, 1
	v_add3_u32 v71, v12, v71, s81
	s_waitcnt vmcnt(12)
	s_cmp_lg_u32 s63, 0
	s_cbranch_scc0 .Lgm__347_3
	v_pk_mul_f32 v[18:19], v[18:19], v[98:99] op_sel:[0,1]
	v_pk_mul_f32 v[16:17], v[16:17], v[98:99] op_sel:[0,1]
.Lgm__347_3:
	v_bfe_u32 v72, v16, 16, 1
	v_lshrrev_b32_e32 v71, 16, v71
	v_add3_u32 v72, v16, v72, s81
	v_and_or_b32 v71, v72, s82, v71
	ds_write2_b32 v88, v2, v71 offset1:16
	v_bfe_u32 v2, v13, 16, 1
	v_add3_u32 v2, v13, v2, s81
	v_bfe_u32 v71, v17, 16, 1
	v_lshrrev_b32_e32 v2, 16, v2
	v_add3_u32 v71, v17, v71, s81
	v_and_or_b32 v2, v71, s82, v2
	ds_write2_b32 v88, v68, v2 offset0:132 offset1:148
	v_bfe_u32 v2, v14, 16, 1
	v_add3_u32 v2, v14, v2, s81
	v_bfe_u32 v68, v18, 16, 1
	v_lshrrev_b32_e32 v2, 16, v2
	v_add3_u32 v68, v18, v68, s81
	v_and_or_b32 v2, v68, s82, v2
	v_add_u32_e32 v68, 0x400, v88
	ds_write2_b32 v68, v69, v2 offset0:8 offset1:24
	v_bfe_u32 v2, v15, 16, 1
	v_add3_u32 v2, v15, v2, s81
	v_bfe_u32 v69, v19, 16, 1
	v_lshrrev_b32_e32 v2, 16, v2
	v_add3_u32 v69, v19, v69, s81
	v_and_or_b32 v2, v69, s82, v2
	ds_write2_b32 v68, v70, v2 offset0:140 offset1:156
	s_waitcnt vmcnt(11)
	s_cmp_lg_u32 s63, 0
	s_cbranch_scc0 .Lgm__347_4
	v_pk_mul_f32 v[22:23], v[22:23], v[100:101] op_sel_hi:[1,0]
	v_pk_mul_f32 v[20:21], v[20:21], v[100:101] op_sel_hi:[1,0]
.Lgm__347_4:
	v_bfe_u32 v2, v20, 16, 1
	v_add3_u32 v2, v20, v2, s81
	s_waitcnt vmcnt(10)
	s_cmp_lg_u32 s63, 0
	s_cbranch_scc0 .Lgm__347_5
	v_pk_mul_f32 v[26:27], v[26:27], v[100:101] op_sel:[0,1]
	v_pk_mul_f32 v[24:25], v[24:25], v[100:101] op_sel:[0,1]
.Lgm__347_5:
	v_bfe_u32 v69, v24, 16, 1
	v_lshrrev_b32_e32 v2, 16, v2
	v_add3_u32 v69, v24, v69, s81
	v_and_or_b32 v2, v69, s82, v2
	v_bfe_u32 v69, v21, 16, 1
	v_add3_u32 v69, v21, v69, s81
	v_bfe_u32 v70, v25, 16, 1
	v_lshrrev_b32_e32 v69, 16, v69
	v_add3_u32 v70, v25, v70, s81
	v_and_or_b32 v69, v70, s82, v69
	v_bfe_u32 v70, v22, 16, 1
	v_add3_u32 v70, v22, v70, s81
	v_bfe_u32 v71, v26, 16, 1
	v_lshrrev_b32_e32 v70, 16, v70
	v_add3_u32 v71, v26, v71, s81
	v_and_or_b32 v70, v71, s82, v70
	v_bfe_u32 v71, v23, 16, 1
	v_add3_u32 v71, v23, v71, s81
	v_bfe_u32 v72, v27, 16, 1
	v_lshrrev_b32_e32 v71, 16, v71
	v_add3_u32 v72, v27, v72, s81
	v_and_or_b32 v71, v72, s82, v71
	s_waitcnt vmcnt(9)
	s_cmp_lg_u32 s63, 0
	s_cbranch_scc0 .Lgm__347_6
	v_pk_mul_f32 v[30:31], v[30:31], v[102:103] op_sel_hi:[1,0]
	v_pk_mul_f32 v[28:29], v[28:29], v[102:103] op_sel_hi:[1,0]
.Lgm__347_6:
	v_bfe_u32 v72, v28, 16, 1
	v_add3_u32 v72, v28, v72, s81
	s_waitcnt vmcnt(8)
	s_cmp_lg_u32 s63, 0
	s_cbranch_scc0 .Lgm__347_7
	v_pk_mul_f32 v[34:35], v[34:35], v[102:103] op_sel:[0,1]
	v_pk_mul_f32 v[32:33], v[32:33], v[102:103] op_sel:[0,1]
.Lgm__347_7:
	v_bfe_u32 v73, v32, 16, 1
	v_lshrrev_b32_e32 v72, 16, v72
	v_add3_u32 v73, v32, v73, s81
	v_and_or_b32 v72, v73, s82, v72
	ds_write2_b32 v88, v2, v72 offset0:32 offset1:48
	v_bfe_u32 v2, v29, 16, 1
	v_add3_u32 v2, v29, v2, s81
	v_bfe_u32 v72, v33, 16, 1
	v_lshrrev_b32_e32 v2, 16, v2
	v_add3_u32 v72, v33, v72, s81
	v_and_or_b32 v2, v72, s82, v2
	ds_write2_b32 v88, v69, v2 offset0:164 offset1:180
	v_bfe_u32 v2, v30, 16, 1
	v_add3_u32 v2, v30, v2, s81
	v_bfe_u32 v69, v34, 16, 1
	v_lshrrev_b32_e32 v2, 16, v2
	v_add3_u32 v69, v34, v69, s81
	v_and_or_b32 v2, v69, s82, v2
	ds_write2_b32 v68, v70, v2 offset0:40 offset1:56
	v_bfe_u32 v2, v31, 16, 1
	v_add3_u32 v2, v31, v2, s81
	v_bfe_u32 v69, v35, 16, 1
	v_lshrrev_b32_e32 v2, 16, v2
	v_add3_u32 v69, v35, v69, s81
	v_and_or_b32 v2, v69, s82, v2
	ds_write2_b32 v68, v71, v2 offset0:172 offset1:188
	s_waitcnt vmcnt(7)
	s_cmp_lg_u32 s63, 0
	s_cbranch_scc0 .Lgm__347_8
	v_pk_mul_f32 v[38:39], v[38:39], v[104:105] op_sel_hi:[1,0]
	v_pk_mul_f32 v[36:37], v[36:37], v[104:105] op_sel_hi:[1,0]
.Lgm__347_8:
	v_bfe_u32 v2, v36, 16, 1
	v_add3_u32 v2, v36, v2, s81
	s_waitcnt vmcnt(6)
	s_cmp_lg_u32 s63, 0
	s_cbranch_scc0 .Lgm__347_9
	v_pk_mul_f32 v[42:43], v[42:43], v[104:105] op_sel:[0,1]
	v_pk_mul_f32 v[40:41], v[40:41], v[104:105] op_sel:[0,1]
; #define LAS __attribute__((address_space(3)))
; __device__ __forceinline__ unsigned pk2(float lo, float hi) { return f2bf(lo) | (f2bf(hi) << 16); }
; __device__ __forceinline__ void tr_to_lds(LAS unsigned* T, int tid, const f32x4 (&v)[8][2]) {
;     const int c4 = (tid & 15) + 16 * ((tid >> 6) & 1), rp = ((tid >> 4) & 3) + 4 * (tid >> 7);
; #pragma unroll
;     for (int i = 0; i < 8; ++i)
; #pragma unroll
;         for (int j = 0; j < 4; ++j) T[(4 * c4 + j) * 132 + 16 * i + rp] = pk2(v[i][0][j], v[i][1][j]);
; __device__ __forceinline__ unsigned conv_claim(unsigned* ctr, volatile LAS unsigned* slot, int limit, int extra, unsigned known, bool peek) {
;     if (peek) known = __hip_atomic_load(ctr, __ATOMIC_RELAXED, __HIP_MEMORY_SCOPE_AGENT);
;     const bool need = (int)known < limit, opt = !need && extra > 0 && (int)known < TL_ALL;
;     unsigned T = 0xffffffffu;
;     if (need || opt) { T = __hip_atomic_fetch_add(ctr, 1u, __ATOMIC_RELAXED, __HIP_MEMORY_SCOPE_AGENT); known = T + 1u; if ((int)T >= TL_ALL) T = 0xffffffffu; }
;     slot[0] = T; slot[1] = need ? 0u : 1u;
.Lgm__347_9:
	v_bfe_u32 v69, v40, 16, 1
	v_lshrrev_b32_e32 v2, 16, v2
	v_add3_u32 v69, v40, v69, s81
	v_and_or_b32 v2, v69, s82, v2
	v_bfe_u32 v69, v37, 16, 1
	v_add3_u32 v69, v37, v69, s81
	v_bfe_u32 v70, v41, 16, 1
	v_lshrrev_b32_e32 v69, 16, v69
	v_add3_u32 v70, v41, v70, s81
	v_and_or_b32 v69, v70, s82, v69
	v_bfe_u32 v70, v38, 16, 1
	v_add3_u32 v70, v38, v70, s81
	v_bfe_u32 v71, v42, 16, 1
	v_lshrrev_b32_e32 v70, 16, v70
	v_add3_u32 v71, v42, v71, s81
	v_and_or_b32 v70, v71, s82, v70
	v_bfe_u32 v71, v39, 16, 1
	v_add3_u32 v71, v39, v71, s81
	v_bfe_u32 v72, v43, 16, 1
	v_lshrrev_b32_e32 v71, 16, v71
	v_add3_u32 v72, v43, v72, s81
	v_and_or_b32 v71, v72, s82, v71
	s_waitcnt vmcnt(5)
	s_cmp_lg_u32 s63, 0
	s_cbranch_scc0 .Lgm__347_10
	v_pk_mul_f32 v[46:47], v[46:47], v[106:107] op_sel_hi:[1,0]
	v_pk_mul_f32 v[44:45], v[44:45], v[106:107] op_sel_hi:[1,0]
.Lgm__347_10:
	v_bfe_u32 v72, v44, 16, 1
	v_add3_u32 v72, v44, v72, s81
	s_waitcnt vmcnt(4)
	s_cmp_lg_u32 s63, 0
	s_cbranch_scc0 .Lgm__347_11
	v_pk_mul_f32 v[50:51], v[50:51], v[106:107] op_sel:[0,1]
	v_pk_mul_f32 v[48:49], v[48:49], v[106:107] op_sel:[0,1]
.Lgm__347_11:
	v_bfe_u32 v73, v48, 16, 1
	v_lshrrev_b32_e32 v72, 16, v72
	v_add3_u32 v73, v48, v73, s81
	v_and_or_b32 v72, v73, s82, v72
	ds_write2_b32 v88, v2, v72 offset0:64 offset1:80
	v_bfe_u32 v2, v45, 16, 1
	v_add3_u32 v2, v45, v2, s81
	v_bfe_u32 v72, v49, 16, 1
	v_lshrrev_b32_e32 v2, 16, v2
	v_add3_u32 v72, v49, v72, s81
	v_and_or_b32 v2, v72, s82, v2
	ds_write2_b32 v88, v69, v2 offset0:196 offset1:212
	v_bfe_u32 v2, v46, 16, 1
	v_add3_u32 v2, v46, v2, s81
	v_bfe_u32 v69, v50, 16, 1
	v_lshrrev_b32_e32 v2, 16, v2
	v_add3_u32 v69, v50, v69, s81
	v_and_or_b32 v2, v69, s82, v2
	ds_write2_b32 v68, v70, v2 offset0:72 offset1:88
	v_bfe_u32 v2, v47, 16, 1
	v_add3_u32 v2, v47, v2, s81
	v_bfe_u32 v69, v51, 16, 1
	v_lshrrev_b32_e32 v2, 16, v2
	v_add3_u32 v69, v51, v69, s81
	v_and_or_b32 v2, v69, s82, v2
	ds_write2_b32 v68, v71, v2 offset0:204 offset1:220
	s_waitcnt vmcnt(3)
	s_cmp_lg_u32 s63, 0
	s_cbranch_scc0 .Lgm__347_12
	v_pk_mul_f32 v[54:55], v[54:55], v[108:109] op_sel_hi:[1,0]
	v_pk_mul_f32 v[52:53], v[52:53], v[108:109] op_sel_hi:[1,0]
.Lgm__347_12:
	v_bfe_u32 v2, v52, 16, 1
	v_add3_u32 v2, v52, v2, s81
	s_waitcnt vmcnt(2)
	s_cmp_lg_u32 s63, 0
	s_cbranch_scc0 .Lgm__347_13
	v_pk_mul_f32 v[58:59], v[58:59], v[108:109] op_sel:[0,1]
	v_pk_mul_f32 v[56:57], v[56:57], v[108:109] op_sel:[0,1]
.Lgm__347_13:
	v_bfe_u32 v69, v56, 16, 1
	v_lshrrev_b32_e32 v2, 16, v2
	v_add3_u32 v69, v56, v69, s81
	v_and_or_b32 v2, v69, s82, v2
	v_bfe_u32 v69, v53, 16, 1
	v_add3_u32 v69, v53, v69, s81
	v_bfe_u32 v70, v57, 16, 1
	v_lshrrev_b32_e32 v69, 16, v69
	v_add3_u32 v70, v57, v70, s81
	v_and_or_b32 v69, v70, s82, v69
	v_bfe_u32 v70, v54, 16, 1
	v_add3_u32 v70, v54, v70, s81
	v_bfe_u32 v71, v58, 16, 1
	v_lshrrev_b32_e32 v70, 16, v70
	v_add3_u32 v71, v58, v71, s81
	v_and_or_b32 v70, v71, s82, v70
	v_bfe_u32 v71, v55, 16, 1
	v_add3_u32 v71, v55, v71, s81
	v_bfe_u32 v72, v59, 16, 1
	v_lshrrev_b32_e32 v71, 16, v71
	v_add3_u32 v72, v59, v72, s81
	v_and_or_b32 v71, v72, s82, v71
	s_waitcnt vmcnt(1)
	s_cmp_lg_u32 s63, 0
	s_cbranch_scc0 .Lgm__347_14
	v_pk_mul_f32 v[62:63], v[62:63], v[110:111] op_sel_hi:[1,0]
	v_pk_mul_f32 v[60:61], v[60:61], v[110:111] op_sel_hi:[1,0]
.Lgm__347_14:
	v_bfe_u32 v72, v60, 16, 1
	v_add3_u32 v72, v60, v72, s81
	s_waitcnt vmcnt(0)
	s_cmp_lg_u32 s63, 0
	s_cbranch_scc0 .Lgm__347_15
	v_pk_mul_f32 v[66:67], v[66:67], v[110:111] op_sel:[0,1]
	v_pk_mul_f32 v[64:65], v[64:65], v[110:111] op_sel:[0,1]
.Lgm__347_15:
	v_bfe_u32 v73, v64, 16, 1
	v_lshrrev_b32_e32 v72, 16, v72
	v_add3_u32 v73, v64, v73, s81
	v_and_or_b32 v72, v73, s82, v72
	ds_write2_b32 v88, v2, v72 offset0:96 offset1:112
	v_bfe_u32 v2, v61, 16, 1
	v_add3_u32 v2, v61, v2, s81
	v_bfe_u32 v72, v65, 16, 1
	v_lshrrev_b32_e32 v2, 16, v2
	v_add3_u32 v72, v65, v72, s81
	v_and_or_b32 v2, v72, s82, v2
	ds_write2_b32 v88, v69, v2 offset0:228 offset1:244
	v_bfe_u32 v2, v62, 16, 1
	v_add3_u32 v2, v62, v2, s81
	v_bfe_u32 v69, v66, 16, 1
	v_lshrrev_b32_e32 v2, 16, v2
	v_add3_u32 v69, v66, v69, s81
	v_and_or_b32 v2, v69, s82, v2
	ds_write2_b32 v68, v70, v2 offset0:104 offset1:120
	v_bfe_u32 v2, v63, 16, 1
	v_add3_u32 v2, v63, v2, s81
	v_bfe_u32 v69, v67, 16, 1
	v_lshrrev_b32_e32 v2, 16, v2
	v_add3_u32 v69, v67, v69, s81
	s_mov_b32 s24, s15
	s_mov_b32 s30, s14
	s_mov_b64 s[6:7], s[0:1]
	s_mov_b32 s22, s19
	s_mov_b32 s25, s34
	s_mov_b32 s23, s20
	v_and_or_b32 v2, v69, s82, v2
	ds_write2_b32 v68, v71, v2 offset0:236 offset1:252
	s_and_saveexec_b64 s[4:5], s[2:3]
	s_cbranch_execz .LBB0_353
	s_cmp_gt_i32 s21, 0
	s_movk_i32 s0, 0x2fa0
	s_cselect_b64 s[8:9], -1, 0
	v_cmp_gt_i32_e64 s[0:1], s0, v76
	v_cmp_gt_i32_e32 vcc, s59, v76
	s_and_b64 s[0:1], s[0:1], s[8:9]
	s_or_b64 s[0:1], vcc, s[0:1]
	v_mov_b32_e32 v2, -1
	s_and_saveexec_b64 s[8:9], s[0:1]
	s_cbranch_execz .LBB0_352
	s_mov_b64 s[12:13], exec
	v_mbcnt_lo_u32_b32 v2, s12, 0
	v_mbcnt_hi_u32_b32 v2, s13, v2
	v_cmp_eq_u32_e64 s[0:1], 0, v2
	s_and_saveexec_b64 s[10:11], s[0:1]
	s_cbranch_execz .LBB0_351
	s_bcnt1_i32_b64 s0, s[12:13]
	v_mov_b32_e32 v68, s0
	v_readlane_b32 s0, v252, 39
	v_readlane_b32 s1, v252, 40
	s_nop 4
	global_atomic_add v68, v3, v68, s[0:1] sc0

; __device__ __forceinline__ void tr_load(const TrJob& jb, int tile, int tid, f32x4 (&v)[8][2], int& k0, int& n0) {
;     const int nblk = (jb.N + 127) / 128, kt = tile / nblk, nt = tile - kt * nblk; k0 = 256 * kt; n0 = 128 * nt;
;     const int c4 = (tid & 15) + 16 * ((tid >> 6) & 1), rp = ((tid >> 4) & 3) + 4 * (tid >> 7);
;     int col = n0 + 4 * c4; col = col < jb.N - 4 ? col : jb.N - 4;
;     const float* wp = jb.W + (size_t)(k0 + 2 * rp) * jb.N + col;
; #pragma unroll
;     for (int i = 0; i < 8; ++i) { v[i][0] = *(const f32x4*)(wp + (size_t)(32 * i) * jb.N); v[i][1] = *(const f32x4*)(wp + (size_t)(32 * i + 1) * jb.N); }
;     if (jb.gain) {
; #pragma unroll
;         for (int i = 0; i < 8; ++i) { const float ga = jb.gain[k0 + 32 * i + 2 * rp], gb = jb.gain[k0 + 32 * i + 2 * rp + 1]; v[i][0] = v[i][0] * ga; v[i][1] = v[i][1] * gb; } }
.LBB0_385:
	s_add_i32 s10, s34, 0x7f
	s_lshr_b32 s10, s10, 7
	v_cvt_f32_u32_e32 v2, s10
	s_sub_i32 s15, 0, s10
	s_abs_i32 s14, s40
	s_ashr_i32 s11, s40, 31
	v_rcp_iflag_f32_e32 v2, v2
	s_nop 0
	v_mul_f32_e32 v2, 0x4f7ffffe, v2
	v_cvt_u32_f32_e32 v2, v2
	s_nop 0
	v_readfirstlane_b32 s16, v2
	s_mul_i32 s15, s15, s16
	s_mul_hi_u32 s15, s16, s15
	s_add_i32 s16, s16, s15
	s_mul_hi_u32 s15, s14, s16
	s_mul_i32 s16, s15, s10
	s_sub_i32 s14, s14, s16
	s_add_i32 s17, s15, 1
	s_sub_i32 s16, s14, s10
	s_cmp_ge_u32 s14, s10
	s_cselect_b32 s15, s17, s15
	s_cselect_b32 s14, s16, s14
	s_add_i32 s16, s15, 1
	s_cmp_ge_u32 s14, s10
	s_cselect_b32 s14, s16, s15
	s_xor_b32 s14, s14, s11
	s_sub_i32 s11, s14, s11
	s_mul_i32 s10, s11, s10
	s_lshl_b32 s14, s11, 8
	s_sub_i32 s10, s40, s10
	v_add_u32_e32 v68, s14, v78
	s_lshl_b32 s15, s10, 7
	s_add_i32 s16, s34, -4
	v_or_b32_e32 v2, s15, v77
	v_mad_u64_u32 v[6:7], s[10:11], v68, s34, 0
	v_ashrrev_i32_e32 v69, 31, v68
	v_min_i32_e32 v4, s16, v2
	v_mov_b32_e32 v2, v7
	v_mad_u64_u32 v[8:9], s[10:11], v69, s34, v[2:3]
	v_mov_b32_e32 v7, v8
	v_lshl_add_u64 v[6:7], v[6:7], 2, s[12:13]
	v_ashrrev_i32_e32 v5, 31, v4
	v_lshl_add_u64 v[4:5], v[4:5], 2, v[6:7]
	s_lshl_b64 s[10:11], s[34:35], 2
	v_lshl_add_u64 v[12:13], v[4:5], 0, s[10:11]
	s_mul_i32 s12, s34, 0x7c
	s_mov_b32 s13, s35
	s_mov_b32 s63, 0
	s_cmp_eq_u64 s[8:9], 0
	s_cbranch_scc1 .Lgf__347_8104
	s_mov_b32 s63, 1
	v_lshl_add_u64 v[112:113], v[68:69], 2, s[8:9]
	global_load_dwordx2 v[96:97], v[112:113], off
	global_load_dwordx2 v[98:99], v[112:113], off offset:128
	global_load_dwordx2 v[100:101], v[112:113], off offset:256
	global_load_dwordx2 v[102:103], v[112:113], off offset:384
	global_load_dwordx2 v[104:105], v[112:113], off offset:512
	global_load_dwordx2 v[106:107], v[112:113], off offset:640
	global_load_dwordx2 v[108:109], v[112:113], off offset:768
	global_load_dwordx2 v[110:111], v[112:113], off offset:896
.Lgf__347_8104:
	global_load_dwordx4 v[4:7], v[4:5], off sc1 nt
	s_nop 0
	global_load_dwordx4 v[8:11], v[12:13], off sc1 nt
	v_lshl_add_u64 v[12:13], v[12:13], 0, s[12:13]
	v_lshl_add_u64 v[20:21], v[12:13], 0, s[10:11]
	global_load_dwordx4 v[12:15], v[12:13], off sc1 nt
	s_nop 0
	global_load_dwordx4 v[16:19], v[20:21], off sc1 nt
	v_lshl_add_u64 v[20:21], v[20:21], 0, s[12:13]
	v_lshl_add_u64 v[28:29], v[20:21], 0, s[10:11]
	global_load_dwordx4 v[20:23], v[20:21], off sc1 nt
	s_nop 0
	global_load_dwordx4 v[24:27], v[28:29], off sc1 nt
	v_lshl_add_u64 v[28:29], v[28:29], 0, s[12:13]
	v_lshl_add_u64 v[36:37], v[28:29], 0, s[10:11]
	v_lshl_add_u64 v[40:41], v[36:37], 0, s[12:13]
	v_lshl_add_u64 v[44:45], v[40:41], 0, s[10:11]
	v_lshl_add_u64 v[48:49], v[44:45], 0, s[12:13]
	v_lshl_add_u64 v[52:53], v[48:49], 0, s[10:11]
	v_lshl_add_u64 v[56:57], v[52:53], 0, s[12:13]
	v_lshl_add_u64 v[60:61], v[56:57], 0, s[10:11]
	v_lshl_add_u64 v[64:65], v[60:61], 0, s[12:13]
	global_load_dwordx4 v[28:31], v[28:29], off sc1 nt
	s_nop 0
	global_load_dwordx4 v[32:35], v[36:37], off sc1 nt
	s_cmp_eq_u64 s[8:9], 0
	global_load_dwordx4 v[36:39], v[40:41], off sc1 nt
	s_nop 0
	global_load_dwordx4 v[40:43], v[44:45], off sc1 nt
	s_nop 0
	global_load_dwordx4 v[44:47], v[48:49], off sc1 nt
	s_nop 0
	global_load_dwordx4 v[48:51], v[52:53], off sc1 nt
	s_nop 0
	global_load_dwordx4 v[52:55], v[56:57], off sc1 nt
	s_nop 0
	global_load_dwordx4 v[56:59], v[60:61], off sc1 nt
	s_nop 0
	global_load_dwordx4 v[60:63], v[64:65], off sc1 nt
	v_lshl_add_u64 v[64:65], v[64:65], 0, s[10:11]
	global_load_dwordx4 v[64:67], v[64:65], off sc1 nt

; __device__ __forceinline__ void tr_load(const TrJob& jb, int tile, int tid, f32x4 (&v)[8][2], int& k0, int& n0) {
;     const int nblk = (jb.N + 127) / 128, kt = tile / nblk, nt = tile - kt * nblk; k0 = 256 * kt; n0 = 128 * nt;
;     const int c4 = (tid & 15) + 16 * ((tid >> 6) & 1), rp = ((tid >> 4) & 3) + 4 * (tid >> 7);
;     int col = n0 + 4 * c4; col = col < jb.N - 4 ? col : jb.N - 4;
;     const float* wp = jb.W + (size_t)(k0 + 2 * rp) * jb.N + col;
; #pragma unroll
;     for (int i = 0; i < 8; ++i) { v[i][0] = *(const f32x4*)(wp + (size_t)(32 * i) * jb.N); v[i][1] = *(const f32x4*)(wp + (size_t)(32 * i + 1) * jb.N); }
;     if (jb.gain) {
; #pragma unroll
;         for (int i = 0; i < 8; ++i) { const float ga = jb.gain[k0 + 32 * i + 2 * rp], gb = jb.gain[k0 + 32 * i + 2 * rp + 1]; v[i][0] = v[i][0] * ga; v[i][1] = v[i][1] * gb; } }
.LBB0_1037:
	s_add_i32 s6, s34, 0x7f
	s_lshr_b32 s6, s6, 7
	v_cvt_f32_u32_e32 v4, s6
	s_sub_i32 s9, 0, s6
	s_abs_i32 s8, s15
	s_ashr_i32 s7, s15, 31
	v_rcp_iflag_f32_e32 v4, v4
	v_lshrrev_b32_e32 v5, 4, v2
	v_ashrrev_i32_e32 v71, 5, v2
	v_bfi_b32 v5, 3, v5, v71
	v_mul_f32_e32 v4, 0x4f7ffffe, v4
	v_cvt_u32_f32_e32 v4, v4
	v_and_b32_e32 v70, 64, v2
	v_lshlrev_b32_e32 v78, 1, v5
	v_readfirstlane_b32 s12, v4
	s_mul_i32 s9, s9, s12
	s_mul_hi_u32 s9, s12, s9
	s_add_i32 s12, s12, s9
	s_mul_hi_u32 s9, s8, s12
	s_mul_i32 s12, s9, s6
	s_sub_i32 s8, s8, s12
	s_add_i32 s13, s9, 1
	s_sub_i32 s12, s8, s6
	s_cmp_ge_u32 s8, s6
	s_cselect_b32 s9, s13, s9
	s_cselect_b32 s8, s12, s8
	s_add_i32 s12, s9, 1
	s_cmp_ge_u32 s8, s6
	s_cselect_b32 s8, s12, s9
	s_xor_b32 s8, s8, s7
	s_sub_i32 s7, s8, s7
	s_mul_i32 s6, s7, s6
	s_sub_i32 s6, s15, s6
	v_lshlrev_b32_e32 v4, 2, v2
	s_lshl_b32 s14, s7, 8
	s_lshl_b32 s15, s6, 7
	v_and_or_b32 v77, v4, 60, v70
	v_or_b32_e32 v4, s15, v77
	s_add_i32 s6, s34, -4
	v_add_u32_e32 v68, s14, v78
	v_min_i32_e32 v4, s6, v4
	s_waitcnt vmcnt(12)
	v_mad_u64_u32 v[6:7], s[6:7], v68, s34, 0
	v_ashrrev_i32_e32 v69, 31, v68
	v_mov_b32_e32 v8, v7
	v_mad_u64_u32 v[8:9], s[6:7], v69, s34, v[8:9]
	v_mov_b32_e32 v7, v8
	v_lshl_add_u64 v[6:7], v[6:7], 2, s[4:5]
	v_ashrrev_i32_e32 v5, 31, v4
	v_lshl_add_u64 v[4:5], v[4:5], 2, v[6:7]
	s_lshl_b64 s[4:5], s[34:35], 2
	s_waitcnt vmcnt(11)
	v_lshl_add_u64 v[12:13], v[4:5], 0, s[4:5]
	s_mul_i32 s6, s34, 0x7c
	s_mov_b32 s7, s35
	s_mov_b32 s32, 0
	s_cmp_eq_u64 s[10:11], 0
	s_cbranch_scc1 .Lgf__1041_22042
	s_mov_b32 s32, 1
	v_lshl_add_u64 v[136:137], v[68:69], 2, s[10:11]
	global_load_dwordx2 v[120:121], v[136:137], off
	global_load_dwordx2 v[122:123], v[136:137], off offset:128
	global_load_dwordx2 v[124:125], v[136:137], off offset:256
	global_load_dwordx2 v[126:127], v[136:137], off offset:384
	global_load_dwordx2 v[128:129], v[136:137], off offset:512
	global_load_dwordx2 v[130:131], v[136:137], off offset:640
	global_load_dwordx2 v[132:133], v[136:137], off offset:768
	global_load_dwordx2 v[134:135], v[136:137], off offset:896

; #define LAS __attribute__((address_space(3)))
; __device__ __forceinline__ unsigned pk2(float lo, float hi) { return f2bf(lo) | (f2bf(hi) << 16); }
; __device__ __forceinline__ void tr_load(const TrJob& jb, int tile, int tid, f32x4 (&v)[8][2], int& k0, int& n0) {
;     ...
;     if (jb.gain) {
; #pragma unroll
;         for (int i = 0; i < 8; ++i) { const float ga = jb.gain[k0 + 32 * i + 2 * rp], gb = jb.gain[k0 + 32 * i + 2 * rp + 1]; v[i][0] = v[i][0] * ga; v[i][1] = v[i][1] * gb; } }
; }
; __device__ __forceinline__ void tr_to_lds(LAS unsigned* T, int tid, const f32x4 (&v)[8][2]) {
;     const int c4 = (tid & 15) + 16 * ((tid >> 6) & 1), rp = ((tid >> 4) & 3) + 4 * (tid >> 7);
; #pragma unroll
;     for (int i = 0; i < 8; ++i)
; #pragma unroll
;         for (int j = 0; j < 4; ++j) T[(4 * c4 + j) * 132 + 16 * i + rp] = pk2(v[i][0][j], v[i][1][j]);
.LBB0_1041:
	s_waitcnt vmcnt(15)
	s_cmp_lg_u32 s32, 0
	s_cbranch_scc0 .Lgm__1041_0
	v_pk_mul_f32 v[6:7], v[6:7], v[120:121] op_sel_hi:[1,0]
	v_pk_mul_f32 v[4:5], v[4:5], v[120:121] op_sel_hi:[1,0]
.Lgm__1041_0:
	v_bfe_u32 v2, v4, 16, 1
	v_add3_u32 v2, v4, v2, s81
	s_waitcnt vmcnt(14)
	s_cmp_lg_u32 s32, 0
	s_cbranch_scc0 .Lgm__1041_1
	v_pk_mul_f32 v[10:11], v[10:11], v[120:121] op_sel:[0,1]
	v_pk_mul_f32 v[8:9], v[8:9], v[120:121] op_sel:[0,1]
.Lgm__1041_1:
	v_bfe_u32 v68, v8, 16, 1
	v_lshrrev_b32_e32 v2, 16, v2
	v_add3_u32 v68, v8, v68, s81
	v_and_or_b32 v2, v68, s82, v2
	v_bfe_u32 v68, v5, 16, 1
	v_add3_u32 v68, v5, v68, s81
	v_bfe_u32 v69, v9, 16, 1
	v_lshrrev_b32_e32 v68, 16, v68
	v_add3_u32 v69, v9, v69, s81
	v_and_or_b32 v68, v69, s82, v68
	v_bfe_u32 v69, v6, 16, 1
	v_add3_u32 v69, v6, v69, s81
	v_bfe_u32 v70, v10, 16, 1
	v_lshrrev_b32_e32 v69, 16, v69
	v_add3_u32 v70, v10, v70, s81
	v_and_or_b32 v69, v70, s82, v69
	v_bfe_u32 v70, v7, 16, 1
	v_add3_u32 v70, v7, v70, s81
	v_bfe_u32 v71, v11, 16, 1
	v_lshrrev_b32_e32 v70, 16, v70
	v_add3_u32 v71, v11, v71, s81
	v_and_or_b32 v70, v71, s82, v70
	s_waitcnt vmcnt(13)
	s_cmp_lg_u32 s32, 0
	s_cbranch_scc0 .Lgm__1041_2
	v_pk_mul_f32 v[14:15], v[14:15], v[122:123] op_sel_hi:[1,0]
	v_pk_mul_f32 v[12:13], v[12:13], v[122:123] op_sel_hi:[1,0]
.Lgm__1041_2:
	v_bfe_u32 v71, v12, 16, 1
	v_add3_u32 v71, v12, v71, s81
	s_waitcnt vmcnt(12)
	s_cmp_lg_u32 s32, 0
	s_cbranch_scc0 .Lgm__1041_3
	v_pk_mul_f32 v[18:19], v[18:19], v[122:123] op_sel:[0,1]
	v_pk_mul_f32 v[16:17], v[16:17], v[122:123] op_sel:[0,1]
.Lgm__1041_3:
	v_bfe_u32 v72, v16, 16, 1
	v_lshrrev_b32_e32 v71, 16, v71
	v_add3_u32 v72, v16, v72, s81
	v_and_or_b32 v71, v72, s82, v71
	ds_write2_b32 v88, v2, v71 offset1:16
	v_bfe_u32 v2, v13, 16, 1
	v_add3_u32 v2, v13, v2, s81
	v_bfe_u32 v71, v17, 16, 1
	v_lshrrev_b32_e32 v2, 16, v2
	v_add3_u32 v71, v17, v71, s81
	v_and_or_b32 v2, v71, s82, v2
	ds_write2_b32 v88, v68, v2 offset0:132 offset1:148
	v_bfe_u32 v2, v14, 16, 1
	v_add3_u32 v2, v14, v2, s81
	v_bfe_u32 v68, v18, 16, 1
	v_lshrrev_b32_e32 v2, 16, v2
	v_add3_u32 v68, v18, v68, s81
	v_and_or_b32 v2, v68, s82, v2
	v_add_u32_e32 v68, 0x400, v88
	ds_write2_b32 v68, v69, v2 offset0:8 offset1:24
	v_bfe_u32 v2, v15, 16, 1
	v_add3_u32 v2, v15, v2, s81
	v_bfe_u32 v69, v19, 16, 1
	v_lshrrev_b32_e32 v2, 16, v2
	v_add3_u32 v69, v19, v69, s81
	v_and_or_b32 v2, v69, s82, v2
	ds_write2_b32 v68, v70, v2 offset0:140 offset1:156
	s_waitcnt vmcnt(11)
	s_cmp_lg_u32 s32, 0
	s_cbranch_scc0 .Lgm__1041_4
	v_pk_mul_f32 v[22:23], v[22:23], v[124:125] op_sel_hi:[1,0]
	v_pk_mul_f32 v[20:21], v[20:21], v[124:125] op_sel_hi:[1,0]
.Lgm__1041_4:
	v_bfe_u32 v2, v20, 16, 1
	v_add3_u32 v2, v20, v2, s81
	s_waitcnt vmcnt(10)
	s_cmp_lg_u32 s32, 0
	s_cbranch_scc0 .Lgm__1041_5
	v_pk_mul_f32 v[26:27], v[26:27], v[124:125] op_sel:[0,1]
	v_pk_mul_f32 v[24:25], v[24:25], v[124:125] op_sel:[0,1]
.Lgm__1041_5:
	v_bfe_u32 v69, v24, 16, 1
	v_lshrrev_b32_e32 v2, 16, v2
	v_add3_u32 v69, v24, v69, s81
	v_and_or_b32 v2, v69, s82, v2
	v_bfe_u32 v69, v21, 16, 1
	v_add3_u32 v69, v21, v69, s81
	v_bfe_u32 v70, v25, 16, 1
	v_lshrrev_b32_e32 v69, 16, v69
	v_add3_u32 v70, v25, v70, s81
	v_and_or_b32 v69, v70, s82, v69
	v_bfe_u32 v70, v22, 16, 1
	v_add3_u32 v70, v22, v70, s81
	v_bfe_u32 v71, v26, 16, 1
	v_lshrrev_b32_e32 v70, 16, v70
	v_add3_u32 v71, v26, v71, s81
	v_and_or_b32 v70, v71, s82, v70
	v_bfe_u32 v71, v23, 16, 1
	v_add3_u32 v71, v23, v71, s81
	v_bfe_u32 v72, v27, 16, 1
	v_lshrrev_b32_e32 v71, 16, v71
	v_add3_u32 v72, v27, v72, s81
	v_and_or_b32 v71, v72, s82, v71
	s_waitcnt vmcnt(9)
	s_cmp_lg_u32 s32, 0
	s_cbranch_scc0 .Lgm__1041_6
	v_pk_mul_f32 v[30:31], v[30:31], v[126:127] op_sel_hi:[1,0]
	v_pk_mul_f32 v[28:29], v[28:29], v[126:127] op_sel_hi:[1,0]
.Lgm__1041_6:
	v_bfe_u32 v72, v28, 16, 1
	v_add3_u32 v72, v28, v72, s81
	s_waitcnt vmcnt(8)
	s_cmp_lg_u32 s32, 0
	s_cbranch_scc0 .Lgm__1041_7
	v_pk_mul_f32 v[34:35], v[34:35], v[126:127] op_sel:[0,1]
	v_pk_mul_f32 v[32:33], v[32:33], v[126:127] op_sel:[0,1]
.Lgm__1041_7:
	v_bfe_u32 v73, v32, 16, 1
	v_lshrrev_b32_e32 v72, 16, v72
	v_add3_u32 v73, v32, v73, s81
	v_and_or_b32 v72, v73, s82, v72
	ds_write2_b32 v88, v2, v72 offset0:32 offset1:48
	v_bfe_u32 v2, v29, 16, 1
	v_add3_u32 v2, v29, v2, s81
	v_bfe_u32 v72, v33, 16, 1
	v_lshrrev_b32_e32 v2, 16, v2
	v_add3_u32 v72, v33, v72, s81
	v_and_or_b32 v2, v72, s82, v2
	ds_write2_b32 v88, v69, v2 offset0:164 offset1:180
	v_bfe_u32 v2, v30, 16, 1
	v_add3_u32 v2, v30, v2, s81
	v_bfe_u32 v69, v34, 16, 1
	v_lshrrev_b32_e32 v2, 16, v2
	v_add3_u32 v69, v34, v69, s81
	v_and_or_b32 v2, v69, s82, v2
	ds_write2_b32 v68, v70, v2 offset0:40 offset1:56
	v_bfe_u32 v2, v31, 16, 1
	v_add3_u32 v2, v31, v2, s81
	v_bfe_u32 v69, v35, 16, 1
	v_lshrrev_b32_e32 v2, 16, v2
	v_add3_u32 v69, v35, v69, s81
	v_and_or_b32 v2, v69, s82, v2
	ds_write2_b32 v68, v71, v2 offset0:172 offset1:188
	s_waitcnt vmcnt(7)
	s_cmp_lg_u32 s32, 0
	s_cbranch_scc0 .Lgm__1041_8
	v_pk_mul_f32 v[38:39], v[38:39], v[128:129] op_sel_hi:[1,0]
	v_pk_mul_f32 v[36:37], v[36:37], v[128:129] op_sel_hi:[1,0]
.Lgm__1041_8:
	v_bfe_u32 v2, v36, 16, 1
	v_add3_u32 v2, v36, v2, s81
	s_waitcnt vmcnt(6)
	s_cmp_lg_u32 s32, 0
	s_cbranch_scc0 .Lgm__1041_9
	v_pk_mul_f32 v[42:43], v[42:43], v[128:129] op_sel:[0,1]
	v_pk_mul_f32 v[40:41], v[40:41], v[128:129] op_sel:[0,1]
; #define LAS __attribute__((address_space(3)))
; __device__ __forceinline__ unsigned pk2(float lo, float hi) { return f2bf(lo) | (f2bf(hi) << 16); }
; __device__ __forceinline__ void tr_to_lds(LAS unsigned* T, int tid, const f32x4 (&v)[8][2]) {
;     const int c4 = (tid & 15) + 16 * ((tid >> 6) & 1), rp = ((tid >> 4) & 3) + 4 * (tid >> 7);
; #pragma unroll
;     for (int i = 0; i < 8; ++i)
; #pragma unroll
;         for (int j = 0; j < 4; ++j) T[(4 * c4 + j) * 132 + 16 * i + rp] = pk2(v[i][0][j], v[i][1][j]);
; __device__ __forceinline__ unsigned conv_claim(unsigned* ctr, volatile LAS unsigned* slot, int limit, int extra, unsigned known, bool peek) {
;     if (peek) known = __hip_atomic_load(ctr, __ATOMIC_RELAXED, __HIP_MEMORY_SCOPE_AGENT);
;     const bool need = (int)known < limit, opt = !need && extra > 0 && (int)known < TL_ALL;
;     unsigned T = 0xffffffffu;
;     if (need || opt) { T = __hip_atomic_fetch_add(ctr, 1u, __ATOMIC_RELAXED, __HIP_MEMORY_SCOPE_AGENT); known = T + 1u; if ((int)T >= TL_ALL) T = 0xffffffffu; }
;     slot[0] = T; slot[1] = need ? 0u : 1u;
.Lgm__1041_9:
	v_bfe_u32 v69, v40, 16, 1
	v_lshrrev_b32_e32 v2, 16, v2
	v_add3_u32 v69, v40, v69, s81
	v_and_or_b32 v2, v69, s82, v2
	v_bfe_u32 v69, v37, 16, 1
	v_add3_u32 v69, v37, v69, s81
	v_bfe_u32 v70, v41, 16, 1
	v_lshrrev_b32_e32 v69, 16, v69
	v_add3_u32 v70, v41, v70, s81
	v_and_or_b32 v69, v70, s82, v69
	v_bfe_u32 v70, v38, 16, 1
	v_add3_u32 v70, v38, v70, s81
	v_bfe_u32 v71, v42, 16, 1
	v_lshrrev_b32_e32 v70, 16, v70
	v_add3_u32 v71, v42, v71, s81
	v_and_or_b32 v70, v71, s82, v70
	v_bfe_u32 v71, v39, 16, 1
	v_add3_u32 v71, v39, v71, s81
	v_bfe_u32 v72, v43, 16, 1
	v_lshrrev_b32_e32 v71, 16, v71
	v_add3_u32 v72, v43, v72, s81
	v_and_or_b32 v71, v72, s82, v71
	s_waitcnt vmcnt(5)
	s_cmp_lg_u32 s32, 0
	s_cbranch_scc0 .Lgm__1041_10
	v_pk_mul_f32 v[46:47], v[46:47], v[130:131] op_sel_hi:[1,0]
	v_pk_mul_f32 v[44:45], v[44:45], v[130:131] op_sel_hi:[1,0]
.Lgm__1041_10:
	v_bfe_u32 v72, v44, 16, 1
	v_add3_u32 v72, v44, v72, s81
	s_waitcnt vmcnt(4)
	s_cmp_lg_u32 s32, 0
	s_cbranch_scc0 .Lgm__1041_11
	v_pk_mul_f32 v[50:51], v[50:51], v[130:131] op_sel:[0,1]
	v_pk_mul_f32 v[48:49], v[48:49], v[130:131] op_sel:[0,1]
.Lgm__1041_11:
	v_bfe_u32 v73, v48, 16, 1
	v_lshrrev_b32_e32 v72, 16, v72
	v_add3_u32 v73, v48, v73, s81
	v_and_or_b32 v72, v73, s82, v72
	ds_write2_b32 v88, v2, v72 offset0:64 offset1:80
	v_bfe_u32 v2, v45, 16, 1
	v_add3_u32 v2, v45, v2, s81
	v_bfe_u32 v72, v49, 16, 1
	v_lshrrev_b32_e32 v2, 16, v2
	v_add3_u32 v72, v49, v72, s81
	v_and_or_b32 v2, v72, s82, v2
	ds_write2_b32 v88, v69, v2 offset0:196 offset1:212
	v_bfe_u32 v2, v46, 16, 1
	v_add3_u32 v2, v46, v2, s81
	v_bfe_u32 v69, v50, 16, 1
	v_lshrrev_b32_e32 v2, 16, v2
	v_add3_u32 v69, v50, v69, s81
	v_and_or_b32 v2, v69, s82, v2
	ds_write2_b32 v68, v70, v2 offset0:72 offset1:88
	v_bfe_u32 v2, v47, 16, 1
	v_add3_u32 v2, v47, v2, s81
	v_bfe_u32 v69, v51, 16, 1
	v_lshrrev_b32_e32 v2, 16, v2
	v_add3_u32 v69, v51, v69, s81
	v_and_or_b32 v2, v69, s82, v2
	ds_write2_b32 v68, v71, v2 offset0:204 offset1:220
	s_waitcnt vmcnt(3)
	s_cmp_lg_u32 s32, 0
	s_cbranch_scc0 .Lgm__1041_12
	v_pk_mul_f32 v[54:55], v[54:55], v[132:133] op_sel_hi:[1,0]
	v_pk_mul_f32 v[52:53], v[52:53], v[132:133] op_sel_hi:[1,0]
.Lgm__1041_12:
	v_bfe_u32 v2, v52, 16, 1
	v_add3_u32 v2, v52, v2, s81
	s_waitcnt vmcnt(2)
	s_cmp_lg_u32 s32, 0
	s_cbranch_scc0 .Lgm__1041_13
	v_pk_mul_f32 v[58:59], v[58:59], v[132:133] op_sel:[0,1]
	v_pk_mul_f32 v[56:57], v[56:57], v[132:133] op_sel:[0,1]
.Lgm__1041_13:
	v_bfe_u32 v69, v56, 16, 1
	v_lshrrev_b32_e32 v2, 16, v2
	v_add3_u32 v69, v56, v69, s81
	v_and_or_b32 v2, v69, s82, v2
	v_bfe_u32 v69, v53, 16, 1
	v_add3_u32 v69, v53, v69, s81
	v_bfe_u32 v70, v57, 16, 1
	v_lshrrev_b32_e32 v69, 16, v69
	v_add3_u32 v70, v57, v70, s81
	v_and_or_b32 v69, v70, s82, v69
	v_bfe_u32 v70, v54, 16, 1
	v_add3_u32 v70, v54, v70, s81
	v_bfe_u32 v71, v58, 16, 1
	v_lshrrev_b32_e32 v70, 16, v70
	v_add3_u32 v71, v58, v71, s81
	v_and_or_b32 v70, v71, s82, v70
	v_bfe_u32 v71, v55, 16, 1
	v_add3_u32 v71, v55, v71, s81
	v_bfe_u32 v72, v59, 16, 1
	v_lshrrev_b32_e32 v71, 16, v71
	v_add3_u32 v72, v59, v72, s81
	v_and_or_b32 v71, v72, s82, v71
	s_waitcnt vmcnt(1)
	s_cmp_lg_u32 s32, 0
	s_cbranch_scc0 .Lgm__1041_14
	v_pk_mul_f32 v[62:63], v[62:63], v[134:135] op_sel_hi:[1,0]
	v_pk_mul_f32 v[60:61], v[60:61], v[134:135] op_sel_hi:[1,0]
.Lgm__1041_14:
	v_bfe_u32 v72, v60, 16, 1
	v_add3_u32 v72, v60, v72, s81
	s_waitcnt vmcnt(0)
	s_cmp_lg_u32 s32, 0
	s_cbranch_scc0 .Lgm__1041_15
	v_pk_mul_f32 v[66:67], v[66:67], v[134:135] op_sel:[0,1]
	v_pk_mul_f32 v[64:65], v[64:65], v[134:135] op_sel:[0,1]
.Lgm__1041_15:
	v_bfe_u32 v73, v64, 16, 1
	v_lshrrev_b32_e32 v72, 16, v72
	v_add3_u32 v73, v64, v73, s81
	v_and_or_b32 v72, v73, s82, v72
	ds_write2_b32 v88, v2, v72 offset0:96 offset1:112
	v_bfe_u32 v2, v61, 16, 1
	v_add3_u32 v2, v61, v2, s81
	v_bfe_u32 v72, v65, 16, 1
	v_lshrrev_b32_e32 v2, 16, v2
	v_add3_u32 v72, v65, v72, s81
	v_and_or_b32 v2, v72, s82, v2
	ds_write2_b32 v88, v69, v2 offset0:228 offset1:244
	v_bfe_u32 v2, v62, 16, 1
	v_add3_u32 v2, v62, v2, s81
	v_bfe_u32 v69, v66, 16, 1
	v_lshrrev_b32_e32 v2, 16, v2
	v_add3_u32 v69, v66, v69, s81
	v_and_or_b32 v2, v69, s82, v2
	ds_write2_b32 v68, v70, v2 offset0:104 offset1:120
	v_bfe_u32 v2, v63, 16, 1
	v_add3_u32 v2, v63, v2, s81
	v_bfe_u32 v69, v67, 16, 1
	v_lshrrev_b32_e32 v2, 16, v2
	v_add3_u32 v69, v67, v69, s81
	s_mov_b32 s24, s15
	s_mov_b32 s28, s14
	s_mov_b64 s[6:7], s[0:1]
	s_mov_b32 s22, s19
	s_mov_b32 s25, s34
	s_mov_b32 s23, s20
	v_and_or_b32 v2, v69, s82, v2
	ds_write2_b32 v68, v71, v2 offset0:236 offset1:252
	s_and_saveexec_b64 s[4:5], s[2:3]
	s_cbranch_execz .LBB0_1047
	s_cmp_gt_i32 s21, 0
	s_movk_i32 s0, 0x2fa0
	s_cselect_b64 s[8:9], -1, 0
	v_cmp_gt_i32_e64 s[0:1], s0, v76
	v_cmp_gt_i32_e32 vcc, s18, v76
	s_and_b64 s[0:1], s[0:1], s[8:9]
	s_or_b64 s[0:1], vcc, s[0:1]
	v_mov_b32_e32 v2, -1
	s_and_saveexec_b64 s[8:9], s[0:1]
	s_cbranch_execz .LBB0_1046
	s_mov_b64 s[12:13], exec
	v_mbcnt_lo_u32_b32 v2, s12, 0
	v_mbcnt_hi_u32_b32 v2, s13, v2
	v_cmp_eq_u32_e64 s[0:1], 0, v2
	s_and_saveexec_b64 s[10:11], s[0:1]
	s_cbranch_execz .LBB0_1045
	s_bcnt1_i32_b64 s0, s[12:13]
	v_mov_b32_e32 v68, s0
	v_readlane_b32 s0, v252, 39
	v_readlane_b32 s1, v252, 40
	s_nop 4
	global_atomic_add v68, v3, v68, s[0:1] sc0

; __device__ __forceinline__ void tr_load(const TrJob& jb, int tile, int tid, f32x4 (&v)[8][2], int& k0, int& n0) {
;     const int nblk = (jb.N + 127) / 128, kt = tile / nblk, nt = tile - kt * nblk; k0 = 256 * kt; n0 = 128 * nt;
;     const int c4 = (tid & 15) + 16 * ((tid >> 6) & 1), rp = ((tid >> 4) & 3) + 4 * (tid >> 7);
;     int col = n0 + 4 * c4; col = col < jb.N - 4 ? col : jb.N - 4;
;     const float* wp = jb.W + (size_t)(k0 + 2 * rp) * jb.N + col;
; #pragma unroll
;     for (int i = 0; i < 8; ++i) { v[i][0] = *(const f32x4*)(wp + (size_t)(32 * i) * jb.N); v[i][1] = *(const f32x4*)(wp + (size_t)(32 * i + 1) * jb.N); }
;     if (jb.gain) {
; #pragma unroll
;         for (int i = 0; i < 8; ++i) { const float ga = jb.gain[k0 + 32 * i + 2 * rp], gb = jb.gain[k0 + 32 * i + 2 * rp + 1]; v[i][0] = v[i][0] * ga; v[i][1] = v[i][1] * gb; } }
.LBB0_1079:
	s_add_i32 s10, s34, 0x7f
	s_lshr_b32 s10, s10, 7
	v_cvt_f32_u32_e32 v2, s10
	s_sub_i32 s15, 0, s10
	s_abs_i32 s14, s30
	s_ashr_i32 s11, s30, 31
	v_rcp_iflag_f32_e32 v2, v2
	s_nop 0
	v_mul_f32_e32 v2, 0x4f7ffffe, v2
	v_cvt_u32_f32_e32 v2, v2
	s_nop 0
	v_readfirstlane_b32 s16, v2
	s_mul_i32 s15, s15, s16
	s_mul_hi_u32 s15, s16, s15
	s_add_i32 s16, s16, s15
	s_mul_hi_u32 s15, s14, s16
	s_mul_i32 s16, s15, s10
	s_sub_i32 s14, s14, s16
	s_add_i32 s17, s15, 1
	s_sub_i32 s16, s14, s10
	s_cmp_ge_u32 s14, s10
	s_cselect_b32 s15, s17, s15
	s_cselect_b32 s14, s16, s14
	s_add_i32 s16, s15, 1
	s_cmp_ge_u32 s14, s10
	s_cselect_b32 s14, s16, s15
	s_xor_b32 s14, s14, s11
	s_sub_i32 s11, s14, s11
	s_mul_i32 s10, s11, s10
	s_lshl_b32 s14, s11, 8
	s_sub_i32 s10, s30, s10
	v_add_u32_e32 v68, s14, v78
	s_lshl_b32 s15, s10, 7
	s_add_i32 s16, s34, -4
	v_or_b32_e32 v2, s15, v77
	v_mad_u64_u32 v[6:7], s[10:11], v68, s34, 0
	v_ashrrev_i32_e32 v69, 31, v68
	v_min_i32_e32 v4, s16, v2
	v_mov_b32_e32 v2, v7
	v_mad_u64_u32 v[8:9], s[10:11], v69, s34, v[2:3]
	v_mov_b32_e32 v7, v8
	v_lshl_add_u64 v[6:7], v[6:7], 2, s[12:13]
	v_ashrrev_i32_e32 v5, 31, v4
	v_lshl_add_u64 v[4:5], v[4:5], 2, v[6:7]
	s_lshl_b64 s[10:11], s[34:35], 2
	v_lshl_add_u64 v[12:13], v[4:5], 0, s[10:11]
	s_mul_i32 s12, s34, 0x7c
	s_mov_b32 s13, s35
	s_mov_b32 s32, 0
	s_cmp_eq_u64 s[8:9], 0
	s_cbranch_scc1 .Lgf__1041_22908
	s_mov_b32 s32, 1
	v_lshl_add_u64 v[136:137], v[68:69], 2, s[8:9]
	global_load_dwordx2 v[120:121], v[136:137], off
	global_load_dwordx2 v[122:123], v[136:137], off offset:128
	global_load_dwordx2 v[124:125], v[136:137], off offset:256
	global_load_dwordx2 v[126:127], v[136:137], off offset:384
	global_load_dwordx2 v[128:129], v[136:137], off offset:512
	global_load_dwordx2 v[130:131], v[136:137], off offset:640
	global_load_dwordx2 v[132:133], v[136:137], off offset:768
	global_load_dwordx2 v[134:135], v[136:137], off offset:896

; __device__ __forceinline__ void tr_load(const TrJob& jb, int tile, int tid, f32x4 (&v)[8][2], int& k0, int& n0) {
;     const int nblk = (jb.N + 127) / 128, kt = tile / nblk, nt = tile - kt * nblk; k0 = 256 * kt; n0 = 128 * nt;
;     const int c4 = (tid & 15) + 16 * ((tid >> 6) & 1), rp = ((tid >> 4) & 3) + 4 * (tid >> 7);
;     int col = n0 + 4 * c4; col = col < jb.N - 4 ? col : jb.N - 4;
;     const float* wp = jb.W + (size_t)(k0 + 2 * rp) * jb.N + col;
; #pragma unroll
;     for (int i = 0; i < 8; ++i) { v[i][0] = *(const f32x4*)(wp + (size_t)(32 * i) * jb.N); v[i][1] = *(const f32x4*)(wp + (size_t)(32 * i + 1) * jb.N); }
;     if (jb.gain) {
; #pragma unroll
;         for (int i = 0; i < 8; ++i) { const float ga = jb.gain[k0 + 32 * i + 2 * rp], gb = jb.gain[k0 + 32 * i + 2 * rp + 1]; v[i][0] = v[i][0] * ga; v[i][1] = v[i][1] * gb; } }
.LBB0_1614:
	s_add_i32 s6, s34, 0x7f
	s_lshr_b32 s6, s6, 7
	v_cvt_f32_u32_e32 v4, s6
	s_sub_i32 s9, 0, s6
	s_abs_i32 s8, s15
	s_ashr_i32 s7, s15, 31
	v_rcp_iflag_f32_e32 v4, v4
	v_lshrrev_b32_e32 v5, 4, v2
	v_ashrrev_i32_e32 v72, 5, v2
	v_bfi_b32 v5, 3, v5, v72
	v_mul_f32_e32 v4, 0x4f7ffffe, v4
	v_cvt_u32_f32_e32 v4, v4
	v_and_b32_e32 v71, 64, v2
	v_lshlrev_b32_e32 v78, 1, v5
	v_readfirstlane_b32 s12, v4
	s_mul_i32 s9, s9, s12
	s_mul_hi_u32 s9, s12, s9
	s_add_i32 s12, s12, s9
	s_mul_hi_u32 s9, s8, s12
	s_mul_i32 s12, s9, s6
	s_sub_i32 s8, s8, s12
	s_add_i32 s13, s9, 1
	s_sub_i32 s12, s8, s6
	s_cmp_ge_u32 s8, s6
	s_cselect_b32 s9, s13, s9
	s_cselect_b32 s8, s12, s8
	s_add_i32 s12, s9, 1
	s_cmp_ge_u32 s8, s6
	s_cselect_b32 s8, s12, s9
	s_xor_b32 s8, s8, s7
	s_sub_i32 s7, s8, s7
	s_mul_i32 s6, s7, s6
	s_sub_i32 s6, s15, s6
	v_lshlrev_b32_e32 v4, 2, v2
	s_lshl_b32 s14, s7, 8
	s_lshl_b32 s15, s6, 7
	v_and_or_b32 v77, v4, 60, v71
	v_or_b32_e32 v4, s15, v77
	s_add_i32 s6, s34, -4
	v_add_u32_e32 v68, s14, v78
	v_min_i32_e32 v4, s6, v4
	s_waitcnt vmcnt(12)
	v_mad_u64_u32 v[6:7], s[6:7], v68, s34, 0
	v_ashrrev_i32_e32 v69, 31, v68
	v_mov_b32_e32 v8, v7
	v_mad_u64_u32 v[8:9], s[6:7], v69, s34, v[8:9]
	v_mov_b32_e32 v7, v8
	v_lshl_add_u64 v[6:7], v[6:7], 2, s[4:5]
	v_ashrrev_i32_e32 v5, 31, v4
	v_lshl_add_u64 v[4:5], v[4:5], 2, v[6:7]
	s_lshl_b64 s[4:5], s[34:35], 2
	s_waitcnt vmcnt(11)
	v_lshl_add_u64 v[12:13], v[4:5], 0, s[4:5]
	s_mul_i32 s6, s34, 0x7c
	s_mov_b32 s7, s35
	s_mov_b32 s32, 0
	s_cmp_eq_u64 s[10:11], 0
	s_cbranch_scc1 .Lgf__1618_32658
	s_mov_b32 s32, 1
	v_lshl_add_u64 v[136:137], v[68:69], 2, s[10:11]
	global_load_dwordx2 v[120:121], v[136:137], off
	global_load_dwordx2 v[122:123], v[136:137], off offset:128
	global_load_dwordx2 v[124:125], v[136:137], off offset:256
	global_load_dwordx2 v[126:127], v[136:137], off offset:384
	global_load_dwordx2 v[128:129], v[136:137], off offset:512
	global_load_dwordx2 v[130:131], v[136:137], off offset:640
	global_load_dwordx2 v[132:133], v[136:137], off offset:768
	global_load_dwordx2 v[134:135], v[136:137], off offset:896
